# one static s_setprio 1 for waves 4-7 (younger half) in the sparse-attention item loop
# baseline (speedup 1.0000x reference)
; #define TILE_LOAD(SLOT, CC, TT) do { const bf16_t* kp = P.KI + (rowb + 64 * (CC) + 16 * (TT) + r16) * 64 + 8 * g; Bk[SLOT][0] = *(const bf16x8*)kp; Bk[SLOT][1] = *(const bf16x8*)(kp + 32); } while (0)
; __device__ __forceinline__ void attn_item(const Ptrs& P, unsigned char* lds, int b, int tq0, int tid) {
;     const int lane = tid & 63, w = __builtin_amdgcn_readfirstlane(tid >> 6), g = lane >> 4, r16 = lane & 15;
;     constexpr int SP = 264;
;     bf16_t* stg = (bf16_t*)lds;
;     unsigned char* l2 = lds + 135168;
;     unsigned short* sel = (unsigned short*)l2;
;     unsigned* cntw = (unsigned*)(l2 + 2048);
;     unsigned* gte = (unsigned*)(l2 + 2048 + 256);
;     bf16_t* Pm = (bf16_t*)(l2 + 4096);
;     const size_t rowb = (size_t)b * T;
;     const int tmax = tq0 + 3;
;     if (tmax < 256 || (DBG & 4)) {
;         for (int i = tid; i < 1024; i += 512) sel[i] = (unsigned short)(((i & 255) <= tq0 + (i >> 8)) ? (i & 255) : 0);
;         __syncthreads();
;     } else {
;         bf16x8 Aq[4][2]; f32x4 wq[4];
; #pragma unroll
;         for (int q = 0; q < 4; ++q) { const bf16_t* qp = P.QI + (rowb + tq0 + q) * 1024 + r16 * 64 + 8 * g; Aq[q][0] = *(const bf16x8*)qp; Aq[q][1] = *(const bf16x8*)(qp + 32);
;             wq[q] = *(const f32x4*)(P.WI + (rowb + tq0 + q) * 16 + 4 * g); }
;         unsigned* KB = (unsigned*)lds;
;         const int nch = (tmax >> 6) + 1;
;         const int ni = (w < nch) ? ((nch - w + 7) >> 3) : 0;
;         bf16x8 Bk[4][2];
;     ...
;         if (ni > 0) { TILE_LOAD(0, w, 0); TILE_LOAD(1, w, 1); }
; __global__ void __launch_bounds__(512, 2) mega_fwd(Args args) {
;     ...
;                 if (tid == 0) *(volatile int*)(lds + 147712) = (int)atomicAdd(ctl + 64 * b, 1u);
;                 __syncthreads();
;                 const int item = *(volatile int*)(lds + 147712);
;                 if (item >= T / 4) break;
;                 attn_item(P, lds, b, 4 * ((T / 4 - 1) - item), tid);
.Lq_have_item:
	s_movk_i32 s12, 0x800
	s_waitcnt lgkmcnt(0)
	v_cmp_gt_i32_e32 vcc, s12, v0
	s_mov_b64 s[12:13], -1
	s_and_saveexec_b64 s[70:71], vcc
	s_cbranch_execz .LBB0_465
	s_and_saveexec_b64 s[90:91], s[0:1]
	v_mov_b32_e32 v255, 1
	global_atomic_add v254, v165, v255, s[46:47] sc0
	s_mov_b64 exec, s[90:91]
	s_nop 0
	s_nop 0
	s_nop 0
	s_nop 0
	s_nop 0
	s_nop 0
	s_nop 0
	s_nop 0
	v_lshlrev_b32_e32 v64, 2, v0
	v_sub_u32_e32 v124, 0x1ffc, v64
	v_readfirstlane_b32 s63, v188
	s_movk_i32 s12, 0xfc
	s_lshr_b32 s62, s63, 6
	s_cmp_lt_u32 s62, 4
	s_cbranch_scc1 .Lprio_skip
	s_setprio 1
.Lprio_skip:
	v_cmp_lt_u32_e32 vcc, s12, v124
	s_and_saveexec_b64 s[12:13], vcc
	s_xor_b64 s[60:61], exec, s[12:13]
	s_cbranch_execz .LBB0_913
	v_sub_u32_e32 v126, 0x1fff, v64
	v_lshrrev_b32_e32 v125, 6, v126
	v_subrev_u32_e32 v0, s62, v125
	v_add_u32_e32 v65, 8, v0
	v_cmp_le_u32_e32 vcc, s62, v125
	v_cmp_lt_u32_e64 s[12:13], 7, v65
	s_and_b64 s[14:15], vcc, s[12:13]
	s_and_saveexec_b64 s[12:13], s[14:15]
	s_cbranch_execz .LBB0_479
	s_cmp_eq_u32 s96, 1
	s_cbranch_scc1 .Lpro_pf
	s_nop 0
	s_nop 0
	s_nop 0
	s_nop 0
	s_nop 0
	s_nop 0
	s_nop 0
	s_nop 0
	s_nop 0
	s_nop 0
	s_nop 0
	s_nop 0
	s_nop 0
	s_nop 0
	s_and_b32 s14, s63, 0xffffffc0
	v_add_u32_e32 v164, s81, v124
	s_ashr_i32 s15, s14, 31
	v_or_b32_e32 v40, 1, v164
	v_mov_b32_e32 v41, v165
	v_or_b32_e32 v32, 2, v164
	v_mov_b32_e32 v33, v165
	v_or_b32_e32 v34, 3, v164
	v_mov_b32_e32 v35, v165
	v_lshl_add_u64 v[48:49], s[14:15], 0, v[182:183]
	v_lshlrev_b64 v[0:1], 11, v[164:165]
	v_lshlrev_b64 v[8:9], 11, v[40:41]
	v_lshlrev_b64 v[16:17], 11, v[32:33]
	v_lshlrev_b64 v[24:25], 11, v[34:35]
	v_lshlrev_b64 v[34:35], 6, v[34:35]
	v_lshlrev_b64 v[32:33], 6, v[32:33]
	v_lshlrev_b64 v[40:41], 6, v[40:41]
	v_lshlrev_b64 v[42:43], 6, v[164:165]
	v_lshlrev_b64 v[48:49], 7, v[48:49]
	v_lshl_add_u64 v[4:5], v[168:169], 0, v[0:1]
	v_lshl_add_u64 v[12:13], v[168:169], 0, v[8:9]
	v_lshl_add_u64 v[20:21], v[168:169], 0, v[16:17]
	v_lshl_add_u64 v[28:29], v[168:169], 0, v[24:25]
	v_lshl_add_u64 v[34:35], v[170:171], 0, v[34:35]
	v_lshl_add_u64 v[36:37], v[170:171], 0, v[32:33]
	v_lshl_add_u64 v[40:41], v[170:171], 0, v[40:41]
	v_lshl_add_u64 v[44:45], v[170:171], 0, v[42:43]
	v_lshl_add_u64 v[60:61], v[172:173], 0, v[48:49]
	global_load_dwordx4 v[0:3], v[4:5], off
	s_nop 0
	global_load_dwordx4 v[4:7], v[4:5], off offset:64
	s_nop 0
	global_load_dwordx4 v[8:11], v[12:13], off
	s_nop 0
	global_load_dwordx4 v[12:15], v[12:13], off offset:64
	s_nop 0
	global_load_dwordx4 v[16:19], v[20:21], off
	s_nop 0
	global_load_dwordx4 v[20:23], v[20:21], off offset:64
	s_nop 0
	global_load_dwordx4 v[24:27], v[28:29], off
	s_nop 0
	global_load_dwordx4 v[28:31], v[28:29], off offset:64
	s_nop 0
	global_load_dwordx4 v[32:35], v[34:35], off
	s_nop 0
	global_load_dwordx4 v[36:39], v[36:37], off
	s_nop 0
	global_load_dwordx4 v[40:43], v[40:41], off
	s_nop 0
	global_load_dwordx4 v[44:47], v[44:45], off
	s_nop 0
	v_lshrrev_b32_e32 v127, 3, v65
	v_sub_u32_e32 v128, 0x1ffd, v64
	v_sub_u32_e32 v129, 0x1ffe, v64
	v_mov_b64_e32 v[150:151], v[60:61]
	s_mov_b64 s[18:19], 0x1000
	v_lshl_add_u64 v[152:153], v[60:61], 0, s[18:19]
	global_load_dwordx4 v[48:51], v[150:151], off
	global_load_dwordx4 v[52:55], v[150:151], off offset:1024
	global_load_dwordx4 v[56:59], v[150:151], off offset:2048
	global_load_dwordx4 v[60:63], v[150:151], off offset:3072
	global_load_dwordx4 v[64:67], v[152:153], off
	global_load_dwordx4 v[68:71], v[152:153], off offset:1024
	global_load_dwordx4 v[72:75], v[152:153], off offset:2048
	global_load_dwordx4 v[76:79], v[152:153], off offset:3072
	s_mov_b64 s[18:19], 0x10000
	v_lshl_add_u64 v[150:151], v[150:151], 0, s[18:19]
	v_lshl_add_u64 v[152:153], v[152:153], 0, s[18:19]
	s_mov_b32 s20, 0
	v_lshl_add_u32 v130, s62, 8, v203
	v_add_u32_e32 v155, 0x10000, v130
	v_add_u32_e32 v154, s14, v179
	s_nop 0
	v_readfirstlane_b32 s14, v127
